# best plus grid-barrier skip between uq and ukv plus MLA loop back-edge rotation (combination of two earlier neutral edits)
# speedup vs baseline: 1.0035x; 1.0011x over previous
; template <int DQK, bool WIN, int SDEPTH, int NQR> ...
;     ...
;     const int tid = tid_in * 64 + lane_;
;     const int wid = tid >> 6, lane = tid & 63, r32 = lane & 31, hi = lane >> 5;
;     const bf16_t* Qlane = Qw + (size_t)r32 * ldq; const int qpos = qpos0 + r32; (void)qpos;
;     char* V_lds = lds; char* K_lds = lds + 2 * SHM_V;
;     float* ws = (float*)(lds + 2 * SHM_V + 2 * SHM_K) + wid * 64; float* li_l = ws; float* al_l = ws + 32; const float* al_h = al_l + 4 * hi; const float* li_h = li_l + 4 * hi;
;     char* qx = lds + 2 * SHM_V + 2 * SHM_K + 2048 + wid * ((NQ - NQR) * 1024) + lane * 16;
;     float zf = 0.f; asm volatile("" : "+v"(zf));
;     float m_reg = m_init, l_reg = l_init; f32x16 o[4]; bf16x8 qr[NQR];
; #pragma unroll
;     for (int d = 0; d < 4; ++d)
; #pragma unroll
;         for (int r = 0; r < 16; ++r) o[d][r] = zf;
;     __syncthreads();
; #pragma unroll
;     for (int d0 = 0; d0 < NQR; ++d0) qr[d0] = *reinterpret_cast<const bf16x8*>(Qlane + d0 * 16 + hi * 8);
;     if constexpr (NQR < NQ) {
; #pragma unroll
;         for (int d0 = NQR; d0 < NQ; ++d0) *reinterpret_cast<bf16x8*>(qx + (d0 - NQR) * 1024) = *reinterpret_cast<const bf16x8*>(Qlane + d0 * 16 + hi * 8);
;     }
;     const int sr = tid >> 4, sc = (tid & 15) * 8, vst0 = v_st(sr, sc), vst1 = v_st(32 + sr, sc);
;     const int krr = tid >> 3, krc = (tid & 7) * 8;
;     const int vb0 = (int)(uintptr_t)V_lds + v_rd_base(lane);
;     struct { bf16x8 vs0, vs1, ks0, ks1, kr; } sr_[SDEPTH];
;     ...
;     f32x16 pA0, pA1, pB0, pB1; float mnA, mnB, alA, alB; bf16x8 pa0, pa1, pa2, pa3; const int NT = t1 - t0;
;     constexpr int SE = 0, SO = SDEPTH - 1;
; __global__ void __launch_bounds__(NTHREADS, 2) fwd_kernel(Args args) {
;     ...
;                 const int S_ = seq < 2 ? 8192 : 4096, rowbase = seq < 2 ? seq * 8192 : 16384 + (seq - 2) * 4096;
;                 const int qloc = qb * 256 + 32 * wave;
;                 const bf16_t* Ql = QB + (size_t)(rowbase + qloc) * NUQ + h * 192;
;                 const bf16_t* Kn = KVB + (size_t)rowbase * NUKV + h * 256;
;                 const bf16_t* Vh = Kn + 128;
;                 const bf16_t* Krp = KR + (size_t)rowbase * 64;
;                 bf16_t* Ow = OB + (size_t)(rowbase + qloc) * DM + h * 128;
;                 att::attn_unit<192, false, ATTB_SD, ATTB_NQR>(Ql, NUQ, Kn, NUKV, Krp, Vh, NUKV, Ow, DM, 0, S_ / 64, 0, -1e30f, 0.f, (char*)lds, wave);
.LBB0_134:
	s_lshl_b32 s1, s9, 12
	s_and_b32 s29, s20, 15
	s_lshl_b32 s0, s9, 13
	s_addk_i32 s1, 0x2000
	s_cmp_lt_i32 s9, 2
	s_cselect_b32 s33, 0x80, 64
	s_cselect_b32 s0, s0, s1
	s_lshl_b32 s1, s8, 8
	s_add_i32 s1, s1, s27
	s_add_i32 s20, s1, s0
	s_ashr_i32 s21, s20, 31
	s_mul_i32 s8, s20, 0x1800
	s_mul_hi_i32 s1, s20, 0x1800
	s_add_u32 s8, s14, s8
	s_addc_u32 s1, s15, s1
	s_mul_i32 s9, s29, 0x180
	s_add_u32 s8, s8, s9
	v_mbcnt_lo_u32_b32 v1, -1, 0
	v_mbcnt_hi_u32_b32 v1, -1, v1
	s_addc_u32 s9, s1, 0
	v_and_b32_e32 v178, 31, v1
	v_bfe_u32 v179, v1, 5, 1
	v_mul_u32_u24_e32 v192, 0x1800, v178
	v_lshlrev_b32_e32 v2, 4, v179
	v_lshl_add_u64 v[4:5], s[8:9], 0, v[192:193]
	v_mov_b32_e32 v3, v193
	v_mov_b32_e32 v0, v193
	v_lshl_add_u64 v[46:47], v[4:5], 0, v[2:3]
	s_barrier
	global_load_dwordx4 v[10:13], v[46:47], off offset:128
	global_load_dwordx4 v[14:17], v[46:47], off offset:160
	global_load_dwordx4 v[18:21], v[46:47], off offset:192
	global_load_dwordx4 v[22:25], v[46:47], off offset:224
	global_load_dwordx4 v[26:29], v[46:47], off offset:256
	global_load_dwordx4 v[30:33], v[46:47], off offset:288
	global_load_dwordx4 v[34:37], v[46:47], off offset:320
	global_load_dwordx4 v[38:41], v[46:47], off offset:352
	s_ashr_i32 s1, s0, 31
	s_lshl_b64 s[8:9], s[0:1], 13
	v_add_u32_e32 v3, s28, v1
	s_add_u32 s8, s58, s8
	v_ashrrev_i32_e32 v48, 4, v3
	s_addc_u32 s9, s59, s9
	s_lshl_b32 s22, s29, 9
	v_add_u32_e32 v68, 32, v48
	s_add_u32 s8, s8, s22
	v_lshlrev_b32_e32 v70, 3, v1
	v_ashrrev_i32_e32 v69, 31, v68
	s_addc_u32 s9, s9, 0
	s_waitcnt vmcnt(0)
	v_and_b32_e32 v168, 0x78, v70
	v_lshlrev_b64 v[6:7], 13, v[68:69]
	v_lshlrev_b32_e32 v192, 1, v168
	v_lshl_add_u64 v[6:7], s[8:9], 0, v[6:7]
	s_lshl_b64 s[0:1], s[0:1], 7
	v_ashrrev_i32_e32 v50, 3, v3
	v_ashrrev_i32_e32 v49, 31, v48
	v_lshl_add_u64 v[6:7], v[6:7], 0, v[192:193]
	s_add_u32 s22, s50, s0
	v_ashrrev_i32_e32 v51, 31, v50
	v_lshlrev_b64 v[4:5], 13, v[48:49]
	global_load_dwordx4 v[52:55], v[6:7], off offset:256
	global_load_dwordx4 v[60:63], v[6:7], off
	s_addc_u32 s23, s51, s1
	v_lshlrev_b64 v[6:7], 7, v[50:51]
	v_lshl_add_u64 v[4:5], s[8:9], 0, v[4:5]
	v_lshl_add_u64 v[8:9], s[22:23], 0, v[6:7]
	v_lshlrev_b32_e32 v6, 4, v1
	v_lshl_add_u64 v[4:5], v[4:5], 0, v[192:193]
	v_and_b32_e32 v6, 0x70, v6
	v_mov_b32_e32 v7, v193
	global_load_dwordx4 v[42:45], v[4:5], off offset:256
	global_load_dwordx4 v[56:59], v[4:5], off
	v_lshl_add_u64 v[8:9], v[8:9], 0, v[6:7]
	global_load_dwordx4 v[64:67], v[8:9], off
	global_load_dwordx4 v[108:111], v[46:47], off
	global_load_dwordx4 v[104:107], v[46:47], off offset:32
	global_load_dwordx4 v[100:103], v[46:47], off offset:64
	global_load_dwordx4 v[96:99], v[46:47], off offset:96
	v_lshlrev_b32_e32 v49, 7, v3
	v_and_b32_e32 v169, 63, v1
	v_and_b32_e32 v180, 0xffffe000, v49
	s_add_i32 s0, 0, 0x14800
	v_lshlrev_b32_e32 v51, 4, v169
	v_add_u32_e32 v46, s0, v180
	v_add_u32_e32 v186, v46, v51
	s_movk_i32 s31, 0x180
	s_movk_i32 s0, 0x70
	v_mul_u32_u24_e32 v49, 0x180, v178
	v_and_b32_e32 v84, 0x70, v70
	v_or_b32_e32 v85, 32, v2
	v_or_b32_e32 v86, 64, v2
	v_or_b32_e32 v87, 0x60, v2
	v_lshlrev_b32_e32 v1, 1, v1
	v_and_b32_e32 v1, 32, v1
	v_lshl_add_u64 v[172:173], s[22:23], 0, v[6:7]
	v_mov_b32_e32 v7, v0
	v_add_u32_e32 v174, 0x120, v48
	v_add_u32_e32 v176, 0x100, v50
	s_mov_b32 s30, 1
	v_lshl_add_u64 v[170:171], s[8:9], 0, v[192:193]
	v_cmp_gt_u32_e64 s[38:39], 32, v169
	s_waitcnt vmcnt(16)
	ds_write_b128 v186, v[10:13]
	s_waitcnt vmcnt(15)
	ds_write_b128 v186, v[14:17] offset:1024
	s_waitcnt vmcnt(14)
	ds_write_b128 v186, v[18:21] offset:2048
	s_waitcnt vmcnt(13)
	ds_write_b128 v186, v[22:25] offset:3072
	s_waitcnt vmcnt(12)
	ds_write_b128 v186, v[26:29] offset:4096
	s_waitcnt vmcnt(11)
	ds_write_b128 v186, v[30:33] offset:5120
	s_waitcnt vmcnt(10)
	ds_write_b128 v186, v[34:37] offset:6144
	s_waitcnt vmcnt(9)
	ds_write_b128 v186, v[38:41] offset:7168
	v_and_b32_e32 v10, 0xfffff0, v48
	v_lshlrev_b32_e32 v11, 1, v48
	v_and_b32_e32 v14, 0xfffff0, v68
	v_lshlrev_b32_e32 v15, 1, v68
	v_and_or_b32 v10, v11, 8, v10
	v_and_or_b32 v14, v15, 8, v14
	v_lshrrev_b32_e32 v11, 1, v48
	v_lshrrev_b32_e32 v10, 1, v10
	v_bfe_u32 v12, v70, 5, 2
	v_and_b32_e32 v13, 3, v48
	v_lshrrev_b32_e32 v14, 1, v14
	v_or_b32_e32 v10, v10, v12
	v_and_or_b32 v11, v11, 4, v13
	v_or_b32_e32 v12, v14, v12
	v_lshlrev_b32_e32 v10, 9, v10
	v_lshlrev_b32_e32 v11, 6, v11
	v_and_b32_e32 v13, 48, v192
	v_lshlrev_b32_e32 v12, 9, v12
	v_or3_b32 v10, v10, v11, v13
	v_or3_b32 v11, v12, v11, v13
	v_add_u32_e32 v195, 0, v11
	v_lshlrev_b32_e32 v11, 3, v48
	v_add_u32_e32 v191, 0, v10
	v_mul_lo_u32 v10, v48, s31
	v_and_b32_e32 v11, 0x70, v11
	v_xad_u32 v11, v11, v192, v10
	v_add_u32_e32 v196, 0, v11
	v_lshlrev_b32_e32 v11, 3, v68
	v_bitop3_b32 v11, v11, v192, s0 bitop3:0x6c
	s_movk_i32 s0, 0x3000
	v_add3_u32 v10, v10, v11, s0
	v_add_u32_e32 v200, 0, v10
	v_or_b32_e32 v10, 0x100, v6
	v_mul_lo_u32 v11, v50, s31
	v_and_b32_e32 v12, 0x70, v3
	v_xad_u32 v10, v10, v12, v11
	v_add_u32_e32 v202, 0, v10
	v_bitop3_b32 v10, v2, v49, v84 bitop3:0xde
	v_add_u32_e32 v204, 0, v10
	s_waitcnt vmcnt(0)
	s_waitcnt vmcnt(6)
	ds_write_b128 v191, v[42:45]
	ds_write_b128 v195, v[52:55]
	s_waitcnt vmcnt(5)
	ds_write_b128 v196, v[56:59] offset:32768
	ds_write_b128 v200, v[60:63] offset:32768
	s_waitcnt vmcnt(4)
	ds_write_b128 v202, v[64:67] offset:32768
	s_waitcnt lgkmcnt(0)
	s_barrier
; #define MASK(P0, P1, t) do { if constexpr (WIN) { const int kb_ = (t) * KVBLK - qpos + 4 * hi; \
;     _Pragma("unroll") for (int r = 0; r < 16; ++r) { const int d_ = kb_ + CROW0(r); if (d_ > 128 || d_ < -128) P0[r] = -1e30f; if (d_ + 32 > 128 || d_ + 32 < -128) P1[r] = -1e30f; } } } while (0)
; template <int DQK, int NQR> __device__ __forceinline__ void qkt(f32x16& p0, f32x16& p1, const char* Ks, const bf16x8* qr, const char* qx, int r32, int hi) {
;     p0 = f32x16{}; p1 = f32x16{};
; #pragma unroll
;     for (int d0 = 0; d0 < DQK / 16; ++d0) { const int cb = (d0 * 16 + hi * 8) * 2;
;         bf16x8 b0 = *reinterpret_cast<const bf16x8*>(Ks + kswz<DQK>(r32, cb));
;         bf16x8 b1 = *reinterpret_cast<const bf16x8*>(Ks + kswz<DQK>(32 + r32, cb));
;         bf16x8 qv; if (d0 < NQR) qv = qr[d0]; else qv = *reinterpret_cast<const bf16x8*>(qx + (d0 - NQR) * 1024);
;         p0 = __builtin_amdgcn_mfma_f32_32x32x16_bf16(b0, qv, p0, 0, 0, 0);
;         p1 = __builtin_amdgcn_mfma_f32_32x32x16_bf16(b1, qv, p1, 0, 0, 0); }
; }
; template <int DQK, bool WIN, int SDEPTH, int NQR> ...
;     ...
;     qkt<DQK, NQR>(pA0, pA1, K_lds, qr, qx, r32, hi); MASK(pA0, pA1, t0); partialSM(pA0, pA1, m_reg, mnA, alA);
;     SLOAD(SO, kbase + KVBLK); if constexpr (SDEPTH == 2) { if (2 < NT) SLOAD(SE, kbase + 2 * KVBLK); }
	ds_read_b128 v[10:13], v204 offset:32768
	ds_read_b128 v[14:17], v204 offset:45056
	s_waitcnt vmcnt(3) lgkmcnt(1)
	v_mfma_f32_32x32x16_bf16 v[32:47], v[10:13], v[108:111], 0
	v_bitop3_b32 v10, v85, v49, v84 bitop3:0xde
	v_add_u32_e32 v203, 0, v10
	ds_read_b128 v[10:13], v203 offset:32768
	ds_read_b128 v[52:55], v203 offset:45056
	s_movk_i32 s0, 0x80
	v_and_b32_e32 v3, 0x3fffffc0, v3
	v_mov_b32_e32 v6, v0
	v_mov_b32_e32 v183, 0
	s_waitcnt lgkmcnt(2)
	v_mfma_f32_32x32x16_bf16 v[16:31], v[14:17], v[108:111], 0
	s_waitcnt vmcnt(2) lgkmcnt(1)
	v_mfma_f32_32x32x16_bf16 v[32:47], v[10:13], v[104:107], v[32:47]
	v_bitop3_b32 v10, v86, v49, v84 bitop3:0xde
	v_add_u32_e32 v201, 0, v10
	s_waitcnt lgkmcnt(0)
	v_mfma_f32_32x32x16_bf16 v[16:31], v[52:55], v[104:107], v[16:31]
	ds_read_b128 v[10:13], v201 offset:32768
	ds_read_b128 v[52:55], v201 offset:45056
	s_waitcnt vmcnt(1) lgkmcnt(1)
	v_mfma_f32_32x32x16_bf16 v[32:47], v[10:13], v[100:103], v[32:47]
	v_bitop3_b32 v10, v87, v49, v84 bitop3:0xde
	v_add_u32_e32 v198, 0, v10
	v_bitop3_b32 v49, v2, v84, s0 bitop3:0x36
	s_movk_i32 s0, 0xa0
	v_bitop3_b32 v88, v2, v84, s0 bitop3:0x36
	s_movk_i32 s0, 0xc0
	v_bitop3_b32 v89, v2, v84, s0 bitop3:0x36
	s_waitcnt lgkmcnt(0)
	v_mfma_f32_32x32x16_bf16 v[16:31], v[52:55], v[100:103], v[16:31]
	ds_read_b128 v[10:13], v198 offset:32768
	ds_read_b128 v[52:55], v198 offset:45056
	s_movk_i32 s0, 0xe0
	v_bitop3_b32 v90, v2, v84, s0 bitop3:0x36
	s_movk_i32 s0, 0x100
	v_bitop3_b32 v91, v2, v84, s0 bitop3:0x36
	s_movk_i32 s0, 0x120
	v_bitop3_b32 v92, v2, v84, s0 bitop3:0x36
	s_waitcnt vmcnt(0) lgkmcnt(1)
	v_mfma_f32_32x32x16_bf16 v[32:47], v[10:13], v[96:99], v[32:47]
	v_mad_u32_u24 v10, v178, s31, v49
	v_add_u32_e32 v197, 0, v10
	s_add_i32 s0, 0, 0x14000
	v_lshl_add_u32 v93, v3, 2, s0
	s_movk_i32 s0, 0x140
	v_lshlrev_b32_e32 v3, 3, v169
	v_bitop3_b32 v94, v2, v84, s0 bitop3:0x36
	s_waitcnt lgkmcnt(0)
	v_mfma_f32_32x32x16_bf16 v[16:31], v[52:55], v[96:99], v[16:31]
	ds_read_b128 v[10:13], v197 offset:32768
	ds_read_b128 v[52:55], v186
	ds_read_b128 v[56:59], v197 offset:45056
	ds_read_b128 v[60:63], v186 offset:1024
	s_mov_b64 s[0:1], 0x80000
	v_lshl_add_u64 v[14:15], v[4:5], 0, s[0:1]
	s_mov_b64 s[0:1], 0xc0000
	v_add_u32_e32 v181, v93, v2
	s_cmp_lg_u32 0, -1
	s_cselect_b32 s35, 0, 0
	s_waitcnt lgkmcnt(2)
	v_mfma_f32_32x32x16_bf16 v[32:47], v[10:13], v[52:55], v[32:47]
	v_mad_u32_u24 v10, v178, s31, v88
	v_add_u32_e32 v199, 0, v10
	s_add_i32 s22, s33, -3
	v_lshl_add_u32 v182, v178, 2, v93
	s_waitcnt lgkmcnt(1)
	v_mfma_f32_32x32x16_bf16 v[16:31], v[56:59], v[52:55], v[16:31]
	ds_read_b128 v[10:13], v199 offset:32768
	ds_read_b128 v[52:55], v199 offset:45056
	s_waitcnt lgkmcnt(1)
	v_mfma_f32_32x32x16_bf16 v[32:47], v[10:13], v[60:63], v[32:47]
	v_mad_u32_u24 v10, v178, s31, v89
	v_add_u32_e32 v190, 0, v10
	s_waitcnt lgkmcnt(0)
	v_mfma_f32_32x32x16_bf16 v[16:31], v[52:55], v[60:63], v[16:31]
	ds_read_b128 v[10:13], v190 offset:32768
	ds_read_b128 v[52:55], v186 offset:2048
	ds_read_b128 v[56:59], v190 offset:45056
	ds_read_b128 v[60:63], v186 offset:3072
	s_waitcnt lgkmcnt(2)
	v_mfma_f32_32x32x16_bf16 v[32:47], v[10:13], v[52:55], v[32:47]
	v_mad_u32_u24 v10, v178, s31, v90
	v_add_u32_e32 v194, 0, v10
	s_waitcnt lgkmcnt(1)
	v_mfma_f32_32x32x16_bf16 v[16:31], v[56:59], v[52:55], v[16:31]
	ds_read_b128 v[10:13], v194 offset:32768
	ds_read_b128 v[52:55], v194 offset:45056
	s_waitcnt lgkmcnt(1)
	v_mfma_f32_32x32x16_bf16 v[32:47], v[10:13], v[60:63], v[32:47]
	v_mad_u32_u24 v10, v178, s31, v91
	v_add_u32_e32 v187, 0, v10
	s_waitcnt lgkmcnt(0)
	v_mfma_f32_32x32x16_bf16 v[16:31], v[52:55], v[60:63], v[16:31]
	ds_read_b128 v[10:13], v187 offset:32768
	ds_read_b128 v[52:55], v186 offset:4096
	ds_read_b128 v[56:59], v187 offset:45056
	ds_read_b128 v[60:63], v186 offset:5120
	s_waitcnt lgkmcnt(2)
	v_mfma_f32_32x32x16_bf16 v[32:47], v[10:13], v[52:55], v[32:47]
	v_mad_u32_u24 v10, v178, s31, v92
	v_add_u32_e32 v189, 0, v10
	ds_read_b128 v[10:13], v189 offset:32768
	s_waitcnt lgkmcnt(2)
	v_mfma_f32_32x32x16_bf16 v[16:31], v[56:59], v[52:55], v[16:31]
	ds_read_b128 v[52:55], v189 offset:45056
	s_waitcnt lgkmcnt(1)
	v_mfma_f32_32x32x16_bf16 v[32:47], v[10:13], v[60:63], v[32:47]
	v_and_b32_e32 v10, 0xc0, v51
	v_and_or_b32 v51, v3, 24, v10
	v_mad_u32_u24 v10, v178, s31, v94
	v_add_u32_e32 v188, 0, v10
	v_and_b32_e32 v3, 0x100, v3
	v_or3_b32 v51, v51, v1, v3
	v_add_u32_e32 v185, s35, v51
	s_waitcnt lgkmcnt(0)
	v_mfma_f32_32x32x16_bf16 v[16:31], v[52:55], v[60:63], v[16:31]
	v_lshl_add_u64 v[60:61], v[4:5], 0, s[0:1]
	ds_read_b128 v[10:13], v188 offset:32768
	ds_read_b128 v[52:55], v186 offset:6144
	global_load_dwordx4 v[56:59], v[14:15], off offset:256
	s_nop 0
	global_load_dwordx4 v[60:63], v[60:61], off offset:256
	v_add_co_u32_e32 v14, vcc, s91, v4
	s_mov_b32 s0, 0xc0000
	s_nop 0
	v_addc_co_u32_e32 v15, vcc, 0, v5, vcc
	v_add_co_u32_e32 v68, vcc, s0, v4
	s_movk_i32 s0, 0x2000
	s_nop 0
	v_addc_co_u32_e32 v69, vcc, 0, v5, vcc
	global_load_dwordx4 v[64:67], v[14:15], off
	s_nop 0
	global_load_dwordx4 v[68:71], v[68:69], off
	v_add_co_u32_e32 v14, vcc, s0, v8
	s_movk_i32 s0, 0x160
	v_bitop3_b32 v1, v2, v84, s0 bitop3:0x36
	v_mad_u32_u24 v3, v178, s31, v1
	v_addc_co_u32_e32 v15, vcc, 0, v9, vcc
	v_add_u32_e32 v205, 0, v3
	global_load_dwordx4 v[72:75], v[14:15], off
	ds_read_b128 v[76:79], v188 offset:45056
	ds_read_b128 v[80:83], v186 offset:7168
	s_waitcnt lgkmcnt(2)
	v_mfma_f32_32x32x16_bf16 v[32:47], v[10:13], v[52:55], v[32:47]
	ds_read_b128 v[10:13], v205 offset:32768
	v_mov_b32_e32 v3, 0x3000
	v_mad_u32_u24 v3, v178, s31, v3
	s_movk_i32 s0, 0x4000
	v_add_u32_e32 v49, v49, v3
	s_add_i32 s31, s33, -1
	v_mov_b32_e32 v14, v0
	s_waitcnt lgkmcnt(2)
; #define SWAIT() do { if constexpr (SDEPTH == 2) { if constexpr (DQK == 192) asm volatile("s_waitcnt vmcnt(5)" ::: "memory"); else asm volatile("s_waitcnt vmcnt(4)" ::: "memory"); } \
;     else asm volatile("s_waitcnt vmcnt(0)" ::: "memory"); } while (0)
; #define MASK(P0, P1, t) do { if constexpr (WIN) { const int kb_ = (t) * KVBLK - qpos + 4 * hi; \
;     _Pragma("unroll") for (int r = 0; r < 16; ++r) { const int d_ = kb_ + CROW0(r); if (d_ > 128 || d_ < -128) P0[r] = -1e30f; if (d_ + 32 > 128 || d_ + 32 < -128) P1[r] = -1e30f; } } } while (0)
; __device__ __forceinline__ void partialSM(f32x16& p0, f32x16& p1, float& m_reg, float& mn, float& alpha) {
;     float pmax = p0[0];
; #pragma unroll
;     for (int r = 1; r < 16; ++r) pmax = fmaxf(pmax, p0[r]);
; #pragma unroll
;     for (int r = 0; r < 16; ++r) pmax = fmaxf(pmax, p1[r]);
;     { auto rr = __builtin_amdgcn_permlane32_swap(__float_as_uint(pmax), __float_as_uint(pmax), false, false);
;       pmax = fmaxf(__uint_as_float(rr[0]), __uint_as_float(rr[1])); }
;     if (__builtin_expect(__all(pmax - m_reg <= THRL), 1)) { mn = m_reg; alpha = 1.f; }
;     else { mn = fmaxf(m_reg, pmax); alpha = __builtin_amdgcn_exp2f(m_reg - mn); m_reg = mn; }
; #pragma unroll
;     for (int r = 0; r < 16; ++r) p0[r] = p0[r] - mn;
; #pragma unroll
;     for (int r = 0; r < 16; ++r) p1[r] = p1[r] - mn;
; #pragma unroll
;     for (int r = 0; r < 16; ++r) p0[r] = __builtin_amdgcn_exp2f(p0[r]);
; }
; template <int DQK, bool WIN, int SDEPTH, int NQR> ...
;     ...
;     qkt<DQK, NQR>(pA0, pA1, K_lds, qr, qx, r32, hi); MASK(pA0, pA1, t0); partialSM(pA0, pA1, m_reg, mnA, alA);
;     SLOAD(SO, kbase + KVBLK); if constexpr (SDEPTH == 2) { if (2 < NT) SLOAD(SE, kbase + 2 * KVBLK); }
;     SWAIT(); SWRITE(1, SO); __syncthreads();
	v_mfma_f32_32x32x16_bf16 v[16:31], v[76:79], v[52:55], v[16:31]
	ds_read_b128 v[52:55], v205 offset:45056
	v_bitop3_b32 v76, v2, v3, v84 bitop3:0xde
	v_bitop3_b32 v78, v86, v3, v84 bitop3:0xde
	v_add_u32_e32 v86, v90, v3
	v_add_u32_e32 v90, v1, v3
	v_bitop3_b32 v77, v85, v3, v84 bitop3:0xde
	v_bitop3_b32 v79, v87, v3, v84 bitop3:0xde
	s_waitcnt lgkmcnt(1)
	v_mfma_f32_32x32x16_bf16 v[32:47], v[10:13], v[80:83], v[32:47]
	v_add_u32_e32 v84, v88, v3
	v_add_u32_e32 v85, v89, v3
	v_add_u32_e32 v87, v91, v3
	v_add_u32_e32 v88, v92, v3
	v_add_u32_e32 v89, v94, v3
	v_mov_b32_e32 v15, v0
	v_mov_b32_e32 v12, v0
	s_nop 4
	v_max_f32_e32 v1, v33, v33
	v_max_f32_e32 v2, v32, v32
	s_waitcnt lgkmcnt(0)
	v_mfma_f32_32x32x16_bf16 v[16:31], v[52:55], v[80:83], v[16:31]
	v_max_f32_e32 v1, v2, v1
	v_max3_f32 v1, v1, v34, v35
	v_max3_f32 v1, v1, v36, v37
	v_max3_f32 v1, v1, v38, v39
	v_max3_f32 v1, v1, v40, v41
	v_max3_f32 v1, v1, v42, v43
	v_max3_f32 v1, v1, v44, v45
	v_max3_f32 v1, v1, v46, v47
	s_nop 3
	v_max3_f32 v1, v1, v16, v17
	v_max3_f32 v1, v1, v18, v19
	v_max3_f32 v1, v1, v20, v21
	v_max3_f32 v1, v1, v22, v23
	v_max3_f32 v1, v1, v24, v25
	v_max3_f32 v1, v1, v26, v27
	v_max3_f32 v1, v1, v28, v29
	v_max3_f32 v1, v1, v30, v31
	v_mov_b32_e32 v2, v1
	s_nop 1
	v_permlane32_swap_b32_e32 v1, v2
	v_max_f32_e32 v2, v2, v2
	v_max_f32_e32 v1, v1, v1
	v_max_f32_e32 v52, v1, v2
	v_add_co_u32_e64 v2, s[0:1], s0, v8
	v_add_f32_e32 v1, 0x7149f2ca, v52
	s_nop 0
	v_addc_co_u32_e64 v3, s[0:1], 0, v9, s[0:1]
	s_mov_b64 s[0:1], 0x140000
	global_load_dwordx4 v[112:115], v[2:3], off
	v_lshl_add_u64 v[2:3], v[4:5], 0, s[0:1]
	s_mov_b32 s0, 0x140000
	v_add_co_u32_e64 v8, s[0:1], s0, v4
	v_cmp_ge_f32_e32 vcc, s90, v1
	s_nop 0
	v_addc_co_u32_e64 v9, s[0:1], 0, v5, s[0:1]
	s_mov_b64 s[0:1], 0x100000
	s_nop 0
	v_lshl_add_u64 v[10:11], v[4:5], 0, s[0:1]
	s_mov_b32 s0, 0x100000
	v_add_co_u32_e64 v4, s[0:1], s0, v4
	s_cmp_eq_u64 vcc, exec
	s_nop 0
	v_addc_co_u32_e64 v5, s[0:1], 0, v5, s[0:1]
	global_load_dwordx4 v[116:119], v[8:9], off
	global_load_dwordx4 v[128:131], v[2:3], off offset:256
	global_load_dwordx4 v[124:127], v[4:5], off
	global_load_dwordx4 v[120:123], v[10:11], off offset:256
	v_max_f32_e32 v52, 0xf149f2ca, v52
	s_cselect_b64 vcc, -1, 0
	v_cndmask_b32_e32 v160, v52, v231, vcc
	v_sub_f32_e32 v32, v32, v160
	v_exp_f32_e32 v153, v32
	v_sub_f32_e32 v32, v33, v160
	v_exp_f32_e32 v163, v32
	v_sub_f32_e32 v32, v34, v160
	v_exp_f32_e32 v154, v32
	v_sub_f32_e32 v32, v35, v160
	v_exp_f32_e32 v164, v32
	v_sub_f32_e32 v32, v36, v160
	v_exp_f32_e32 v162, v32
	v_sub_f32_e32 v32, v37, v160
	v_exp_f32_e32 v165, v32
	v_sub_f32_e32 v32, v38, v160
	v_exp_f32_e32 v155, v32
	v_sub_f32_e32 v32, v39, v160
	v_exp_f32_e32 v161, v32
	v_sub_f32_e32 v32, v40, v160
	v_exp_f32_e32 v151, v32
	v_sub_f32_e32 v32, v41, v160
	v_exp_f32_e32 v156, v32
	v_sub_f32_e32 v32, v42, v160
	v_exp_f32_e32 v157, v32
	v_sub_f32_e32 v32, v43, v160
	v_exp_f32_e32 v158, v32
	v_sub_f32_e32 v32, v44, v160
	v_exp_f32_e32 v148, v32
	v_sub_f32_e32 v32, v45, v160
	v_sub_f32_e32 v33, 0xf149f2ca, v52
	v_exp_f32_e32 v149, v32
	v_sub_f32_e32 v32, v46, v160
	v_exp_f32_e32 v33, v33
	v_exp_f32_e32 v150, v32
	v_sub_f32_e32 v32, v47, v160
	v_exp_f32_e32 v159, v32
	s_waitcnt vmcnt(5)
	s_addk_i32 s35, 0x4000
	s_waitcnt vmcnt(9)
	ds_write_b128 v191, v[56:59] offset:16384
	s_waitcnt vmcnt(8)
	ds_write_b128 v195, v[60:63] offset:16384
	s_waitcnt vmcnt(7)
	ds_write_b128 v196, v[64:67] offset:57344
	s_waitcnt vmcnt(6)
	ds_write_b128 v200, v[68:71] offset:57344
	s_waitcnt vmcnt(5)
	ds_write_b128 v202, v[72:75] offset:57344
	v_mov_b32_e32 v1, v0
	v_mov_b32_e32 v2, v0
	v_mov_b32_e32 v3, v0
	v_mov_b32_e32 v4, v0
	v_mov_b32_e32 v5, v0
	v_mov_b32_e32 v8, v0
	v_mov_b32_e32 v9, v0
	v_mov_b32_e32 v10, v0
	v_mov_b32_e32 v11, v0
	v_mov_b32_e32 v13, v0
	v_cndmask_b32_e64 v217, v33, 1.0, vcc
	v_sub_f32_e32 v144, v16, v160
	v_sub_f32_e32 v145, v17, v160
	v_sub_f32_e32 v146, v18, v160
	v_sub_f32_e32 v147, v19, v160
	v_sub_f32_e32 v136, v20, v160
	v_sub_f32_e32 v137, v21, v160
	v_sub_f32_e32 v138, v22, v160
	v_sub_f32_e32 v139, v23, v160
	v_sub_f32_e32 v140, v24, v160
	v_sub_f32_e32 v141, v25, v160
	v_sub_f32_e32 v142, v26, v160
	v_sub_f32_e32 v143, v27, v160
	v_sub_f32_e32 v132, v28, v160
	v_sub_f32_e32 v133, v29, v160
	v_sub_f32_e32 v134, v30, v160
	v_sub_f32_e32 v135, v31, v160
	v_add_u32_e32 v184, s35, v51
	v_add_u32_e32 v212, 0, v49
	v_mov_b64_e32 v[62:63], v[14:15]
	v_mov_b64_e32 v[46:47], v[14:15]
	v_mov_b64_e32 v[30:31], v[14:15]
	v_add_u32_e32 v216, 0, v76
	v_add_u32_e32 v215, 0, v77
	v_add_u32_e32 v214, 0, v78
	v_add_u32_e32 v213, 0, v79
	v_add_u32_e32 v211, 0, v84
	v_add_u32_e32 v210, 0, v85
	v_add_u32_e32 v209, 0, v86
	v_add_u32_e32 v208, 0, v87
	v_add_u32_e32 v207, 0, v88
	v_add_u32_e32 v206, 0, v89
	v_add_u32_e32 v192, 0, v90
	v_mov_b64_e32 v[60:61], v[12:13]
	v_mov_b64_e32 v[58:59], v[10:11]
	v_mov_b64_e32 v[56:57], v[8:9]
	v_mov_b64_e32 v[54:55], v[6:7]
	v_mov_b64_e32 v[52:53], v[4:5]
	v_mov_b64_e32 v[50:51], v[2:3]
	v_mov_b64_e32 v[48:49], v[0:1]
	v_mov_b64_e32 v[44:45], v[12:13]
	v_mov_b64_e32 v[42:43], v[10:11]
	v_mov_b64_e32 v[40:41], v[8:9]
	v_mov_b64_e32 v[38:39], v[6:7]
	v_mov_b64_e32 v[36:37], v[4:5]
	v_mov_b64_e32 v[34:35], v[2:3]
	v_mov_b64_e32 v[32:33], v[0:1]
	v_mov_b64_e32 v[28:29], v[12:13]
	v_mov_b64_e32 v[26:27], v[10:11]
	v_mov_b64_e32 v[24:25], v[8:9]
	v_mov_b64_e32 v[22:23], v[6:7]
	v_mov_b64_e32 v[20:21], v[4:5]
	v_mov_b64_e32 v[18:19], v[2:3]
	v_mov_b64_e32 v[16:17], v[0:1]
	s_waitcnt lgkmcnt(0)
.Lmla_head:
	s_barrier
; #define SBAR() __builtin_amdgcn_sched_barrier(0)
; #define MASK(P0, P1, t) do { if constexpr (WIN) { const int kb_ = (t) * KVBLK - qpos + 4 * hi; \
;     _Pragma("unroll") for (int r = 0; r < 16; ++r) { const int d_ = kb_ + CROW0(r); if (d_ > 128 || d_ < -128) P0[r] = -1e30f; if (d_ + 32 > 128 || d_ + 32 < -128) P1[r] = -1e30f; } } } while (0)
; __device__ __forceinline__ void finishSM(f32x16& p0, f32x16& p1, float alpha, float& l_reg, bf16x8& pa0, bf16x8& pa1, bf16x8& pa2, bf16x8& pa3) {
; #pragma unroll
;     for (int r = 0; r < 16; ++r) p1[r] = __builtin_amdgcn_exp2f(p1[r]);
;     float ps = 0;
; #pragma unroll
;     for (int r = 0; r < 16; ++r) ps += p0[r];
; #pragma unroll
;     for (int r = 0; r < 16; ++r) ps += p1[r];
; template <int DQK, bool WIN, int SDEPTH, int NQR> ...
;     ...
;     for (int j = 1; j + 1 < NT; j += 2) {
;         SBAR(); qkt<DQK, NQR>(pB0, pB1, K_lds + SHM_K, qr, qx, r32, hi); MASK(pB0, pB1, t0 + j);
;         finishSM(pA0, pA1, alA, l_reg, pa0, pa1, pa2, pa3); SBAR();
.LBB0_135:
	ds_read_b128 v[64:67], v204 offset:57344
	ds_read_b128 v[68:71], v216 offset:57344
	ds_read_b128 v[218:221], v203 offset:57344
	ds_read_b128 v[222:225], v215 offset:57344
	v_add_f32_e32 v152, 0, v153
	v_add_f32_e32 v152, v163, v152
	s_waitcnt lgkmcnt(3)
	v_mfma_f32_32x32x16_bf16 v[80:95], v[64:67], v[108:111], 0
	v_add_f32_e32 v152, v154, v152
	v_add_f32_e32 v152, v164, v152
	v_add_f32_e32 v152, v162, v152
	v_add_f32_e32 v152, v165, v152
	v_add_f32_e32 v152, v155, v152
	v_add_f32_e32 v152, v161, v152
	v_add_f32_e32 v152, v151, v152
	s_waitcnt lgkmcnt(2)
	v_mfma_f32_32x32x16_bf16 v[64:79], v[68:71], v[108:111], 0
	v_add_f32_e32 v152, v156, v152
	v_add_f32_e32 v152, v157, v152
	v_add_f32_e32 v152, v158, v152
	v_exp_f32_e32 v144, v144
	v_add_f32_e32 v152, v148, v152
	v_exp_f32_e32 v145, v145
	v_add_f32_e32 v152, v149, v152
	s_waitcnt lgkmcnt(1)
	v_mfma_f32_32x32x16_bf16 v[80:95], v[218:221], v[104:107], v[80:95]
	v_exp_f32_e32 v146, v146
	v_add_f32_e32 v152, v150, v152
	v_exp_f32_e32 v147, v147
	v_add_f32_e32 v152, v159, v152
	v_exp_f32_e32 v136, v136
	v_add_f32_e32 v152, v144, v152
	v_exp_f32_e32 v137, v137
	s_waitcnt lgkmcnt(0)
	v_mfma_f32_32x32x16_bf16 v[64:79], v[222:225], v[104:107], v[64:79]
	ds_read_b128 v[218:221], v201 offset:57344
	ds_read_b128 v[222:225], v214 offset:57344
	v_add_f32_e32 v152, v145, v152
	v_exp_f32_e32 v138, v138
	v_add_f32_e32 v152, v146, v152
	v_exp_f32_e32 v139, v139
	v_add_f32_e32 v152, v147, v152
	v_exp_f32_e32 v140, v140
	s_waitcnt lgkmcnt(1)
	v_mfma_f32_32x32x16_bf16 v[80:95], v[218:221], v[100:103], v[80:95]
	v_add_f32_e32 v152, v136, v152
	v_exp_f32_e32 v141, v141
	v_add_f32_e32 v152, v137, v152
	v_exp_f32_e32 v142, v142
	v_add_f32_e32 v152, v138, v152
	v_exp_f32_e32 v143, v143
	v_add_f32_e32 v152, v139, v152
	s_waitcnt lgkmcnt(0)
	v_mfma_f32_32x32x16_bf16 v[64:79], v[222:225], v[100:103], v[64:79]
	ds_read_b128 v[218:221], v198 offset:57344
	ds_read_b128 v[222:225], v213 offset:57344
	v_exp_f32_e32 v132, v132
	v_add_f32_e32 v152, v140, v152
	v_exp_f32_e32 v133, v133
	v_add_f32_e32 v152, v141, v152
	v_exp_f32_e32 v134, v134
	v_add_f32_e32 v152, v142, v152
	s_waitcnt lgkmcnt(1)
	v_mfma_f32_32x32x16_bf16 v[80:95], v[218:221], v[96:99], v[80:95]
	v_exp_f32_e32 v135, v135
	v_add_f32_e32 v152, v143, v152
	v_add_f32_e32 v152, v132, v152
	v_add_f32_e32 v152, v133, v152
	v_add_f32_e32 v152, v134, v152
	s_waitcnt lgkmcnt(0)
	v_mfma_f32_32x32x16_bf16 v[64:79], v[222:225], v[96:99], v[64:79]
	ds_read_b128 v[218:221], v197 offset:57344
	ds_read_b128 v[222:225], v212 offset:57344
	ds_read_b128 v[226:229], v186
	s_waitcnt lgkmcnt(0)
	v_mfma_f32_32x32x16_bf16 v[80:95], v[218:221], v[226:229], v[80:95]
	v_mfma_f32_32x32x16_bf16 v[64:79], v[222:225], v[226:229], v[64:79]
	ds_read_b128 v[218:221], v199 offset:57344
	ds_read_b128 v[222:225], v211 offset:57344
	ds_read_b128 v[226:229], v186 offset:1024
	s_waitcnt lgkmcnt(0)
	v_mfma_f32_32x32x16_bf16 v[80:95], v[218:221], v[226:229], v[80:95]
	v_mfma_f32_32x32x16_bf16 v[64:79], v[222:225], v[226:229], v[64:79]
	ds_read_b128 v[218:221], v190 offset:57344
	ds_read_b128 v[222:225], v210 offset:57344
	ds_read_b128 v[226:229], v186 offset:2048
	s_waitcnt lgkmcnt(0)
	v_mfma_f32_32x32x16_bf16 v[80:95], v[218:221], v[226:229], v[80:95]
	v_mfma_f32_32x32x16_bf16 v[64:79], v[222:225], v[226:229], v[64:79]
	ds_read_b128 v[218:221], v194 offset:57344
	ds_read_b128 v[222:225], v209 offset:57344
	ds_read_b128 v[226:229], v186 offset:3072
	s_waitcnt lgkmcnt(0)
	v_mfma_f32_32x32x16_bf16 v[80:95], v[218:221], v[226:229], v[80:95]
	v_mfma_f32_32x32x16_bf16 v[64:79], v[222:225], v[226:229], v[64:79]
	ds_read_b128 v[218:221], v187 offset:57344
	ds_read_b128 v[222:225], v208 offset:57344
	ds_read_b128 v[226:229], v186 offset:4096
	s_waitcnt lgkmcnt(0)
	v_mfma_f32_32x32x16_bf16 v[80:95], v[218:221], v[226:229], v[80:95]
	v_mfma_f32_32x32x16_bf16 v[64:79], v[222:225], v[226:229], v[64:79]
	ds_read_b128 v[218:221], v189 offset:57344
	ds_read_b128 v[222:225], v207 offset:57344
	ds_read_b128 v[226:229], v186 offset:5120
	s_waitcnt lgkmcnt(0)
	v_mfma_f32_32x32x16_bf16 v[80:95], v[218:221], v[226:229], v[80:95]
	v_mfma_f32_32x32x16_bf16 v[64:79], v[222:225], v[226:229], v[64:79]
	ds_read_b128 v[218:221], v188 offset:57344
	ds_read_b128 v[222:225], v206 offset:57344
	ds_read_b128 v[226:229], v186 offset:6144
	s_waitcnt lgkmcnt(0)
	v_mfma_f32_32x32x16_bf16 v[80:95], v[218:221], v[226:229], v[80:95]
	v_mfma_f32_32x32x16_bf16 v[64:79], v[222:225], v[226:229], v[64:79]
	ds_read_b128 v[218:221], v205 offset:57344
	ds_read_b128 v[222:225], v192 offset:57344
	ds_read_b128 v[226:229], v186 offset:7168
	s_waitcnt lgkmcnt(0)
; #define SBAR() __builtin_amdgcn_sched_barrier(0)
; __device__ __forceinline__ void finishSM(f32x16& p0, f32x16& p1, float alpha, float& l_reg, bf16x8& pa0, bf16x8& pa1, bf16x8& pa2, bf16x8& pa3) {
;     ...
;     PK4(p0, 0, pa0); PK4(p0, 8, pa1); PK4(p1, 0, pa2); PK4(p1, 8, pa3);
; template <int D0> __device__ __forceinline__ void pv_one(f32x16& od, int vb, bf16x8 pa0, bf16x8 pa1, bf16x8 pa2, bf16x8 pa3) {
;     const s16x4 l0 = tr_read<v_rd_off(D0, 0, 0)>(vb), h0 = tr_read<v_rd_off(D0, 0, 1)>(vb), l1 = tr_read<v_rd_off(D0, 1, 0)>(vb), h1 = tr_read<v_rd_off(D0, 1, 1)>(vb);
;     const s16x4 l2 = tr_read<v_rd_off(D0, 2, 0)>(vb), h2 = tr_read<v_rd_off(D0, 2, 1)>(vb), l3 = tr_read<v_rd_off(D0, 3, 0)>(vb), h3 = tr_read<v_rd_off(D0, 3, 1)>(vb);
;     asm volatile("s_waitcnt lgkmcnt(0)" ::: "memory"); SBAR();
;     ...
;     od = __builtin_amdgcn_mfma_f32_32x32x16_bf16(pa0, PK(l0, h0), od, 0, 0, 0);
;     od = __builtin_amdgcn_mfma_f32_32x32x16_bf16(pa1, PK(l1, h1), od, 0, 0, 0);
;     od = __builtin_amdgcn_mfma_f32_32x32x16_bf16(pa2, PK(l2, h2), od, 0, 0, 0);
;     od = __builtin_amdgcn_mfma_f32_32x32x16_bf16(pa3, PK(l3, h3), od, 0, 0, 0);
;     ...
; }
; __device__ __forceinline__ void pv_d0(f32x16* o, int vb, bf16x8 pa0, bf16x8 pa1, bf16x8 pa2, bf16x8 pa3) {
;     pv_one<0>(o[0], vb, pa0, pa1, pa2, pa3); pv_one<1>(o[1], vb, pa0, pa1, pa2, pa3); pv_one<2>(o[2], vb, pa0, pa1, pa2, pa3); pv_one<3>(o[3], vb, pa0, pa1, pa2, pa3);
; }
	v_mfma_f32_32x32x16_bf16 v[80:95], v[218:221], v[226:229], v[80:95]
	v_add_f32_e32 v218, v135, v152
	v_mov_b32_e32 v219, v218
	v_cvt_pk_bf16_f32 v152, v153, v163
	v_cvt_pk_bf16_f32 v153, v154, v164
	v_cvt_pk_bf16_f32 v154, v162, v165
	v_cvt_pk_bf16_f32 v155, v155, v161
	v_cvt_pk_bf16_f32 v156, v151, v156
	v_mfma_f32_32x32x16_bf16 v[64:79], v[222:225], v[226:229], v[64:79]
	v_cvt_pk_bf16_f32 v157, v157, v158
	v_cvt_pk_bf16_f32 v158, v148, v149
	v_cvt_pk_bf16_f32 v159, v150, v159
	v_cvt_pk_bf16_f32 v162, v144, v145
	v_cvt_pk_bf16_f32 v163, v146, v147
	v_cvt_pk_bf16_f32 v164, v136, v137
	v_cvt_pk_bf16_f32 v165, v138, v139
	v_cvt_pk_bf16_f32 v220, v140, v141
	v_cvt_pk_bf16_f32 v221, v142, v143
	v_cvt_pk_bf16_f32 v222, v132, v133
	s_nop 0
	v_permlane32_swap_b32_e32 v218, v219
	v_permlane32_swap_b32_e32 v152, v154
	v_cvt_pk_bf16_f32 v223, v134, v135
	v_permlane32_swap_b32_e32 v220, v222
	v_permlane32_swap_b32_e32 v153, v155
	v_permlane32_swap_b32_e32 v156, v158
	v_permlane32_swap_b32_e32 v157, v159
	v_permlane32_swap_b32_e32 v162, v164
	v_permlane32_swap_b32_e32 v163, v165
	v_permlane32_swap_b32_e32 v221, v223
	v_add_u32_e32 v132, 0xffffffa0, v174
	v_ashrrev_i32_e32 v133, 31, v132
	v_lshlrev_b64 v[132:133], 13, v[132:133]
	v_lshl_add_u64 v[136:137], v[170:171], 0, v[132:133]
	v_subrev_u32_e32 v132, 64, v174
	v_ashrrev_i32_e32 v133, 31, v132
	v_lshlrev_b64 v[132:133], 13, v[132:133]
	v_subrev_u32_e32 v148, 64, v176
	v_lshl_add_u64 v[140:141], v[170:171], 0, v[132:133]
	v_ashrrev_i32_e32 v149, 31, v148
	global_load_dwordx4 v[132:135], v[136:137], off offset:256
	s_nop 0
	global_load_dwordx4 v[136:139], v[136:137], off
	s_nop 0
	global_load_dwordx4 v[144:147], v[140:141], off offset:256
	s_nop 0
	global_load_dwordx4 v[140:143], v[140:141], off
	v_lshlrev_b64 v[148:149], 7, v[148:149]
	v_lshl_add_u64 v[148:149], v[172:173], 0, v[148:149]
	global_load_dwordx4 v[148:151], v[148:149], off
	ds_read_b64_tr_b16 v[224:225], v185 offset:0
	ds_read_b64_tr_b16 v[226:227], v185 offset:0x800
	ds_read_b64_tr_b16 v[232:233], v185 offset:0x1000
	ds_read_b64_tr_b16 v[234:235], v185 offset:0x1800
	ds_read_b64_tr_b16 v[236:237], v185 offset:0x2000
	ds_read_b64_tr_b16 v[238:239], v185 offset:0x2800
	ds_read_b64_tr_b16 v[240:241], v185 offset:0x3000
	ds_read_b64_tr_b16 v[242:243], v185 offset:0x3800
	s_waitcnt lgkmcnt(0)
	s_nop 0
	v_mfma_f32_32x32x16_bf16 v[0:15], v[152:155], v[224:227], v[0:15]
	ds_read_b64_tr_b16 v[224:225], v185 offset:0x200
	ds_read_b64_tr_b16 v[226:227], v185 offset:0xa00
	v_mfma_f32_32x32x16_bf16 v[0:15], v[156:159], v[232:235], v[0:15]
	ds_read_b64_tr_b16 v[232:233], v185 offset:0x1200
	ds_read_b64_tr_b16 v[234:235], v185 offset:0x1a00
	v_mfma_f32_32x32x16_bf16 v[0:15], v[162:165], v[236:239], v[0:15]
	ds_read_b64_tr_b16 v[236:237], v185 offset:0x2200
	ds_read_b64_tr_b16 v[238:239], v185 offset:0x2a00
	v_mfma_f32_32x32x16_bf16 v[0:15], v[220:223], v[240:243], v[0:15]
	ds_read_b64_tr_b16 v[240:241], v185 offset:0x3200
	ds_read_b64_tr_b16 v[242:243], v185 offset:0x3a00
	s_waitcnt lgkmcnt(0)
	v_mfma_f32_32x32x16_bf16 v[48:63], v[152:155], v[224:227], v[48:63]
	ds_read_b64_tr_b16 v[224:225], v185 offset:0x400
	ds_read_b64_tr_b16 v[226:227], v185 offset:0xc00
	v_mfma_f32_32x32x16_bf16 v[48:63], v[156:159], v[232:235], v[48:63]
	ds_read_b64_tr_b16 v[232:233], v185 offset:0x1400
	ds_read_b64_tr_b16 v[234:235], v185 offset:0x1c00
	v_mfma_f32_32x32x16_bf16 v[48:63], v[162:165], v[236:239], v[48:63]
	ds_read_b64_tr_b16 v[236:237], v185 offset:0x2400
	ds_read_b64_tr_b16 v[238:239], v185 offset:0x2c00
	v_mfma_f32_32x32x16_bf16 v[48:63], v[220:223], v[240:243], v[48:63]
	ds_read_b64_tr_b16 v[240:241], v185 offset:0x3400
	ds_read_b64_tr_b16 v[242:243], v185 offset:0x3c00
	s_waitcnt lgkmcnt(0)
	v_mfma_f32_32x32x16_bf16 v[32:47], v[152:155], v[224:227], v[32:47]
	ds_read_b64_tr_b16 v[224:225], v185 offset:0x600
	ds_read_b64_tr_b16 v[226:227], v185 offset:0xe00
	v_mfma_f32_32x32x16_bf16 v[32:47], v[156:159], v[232:235], v[32:47]
	ds_read_b64_tr_b16 v[232:233], v185 offset:0x1600
	ds_read_b64_tr_b16 v[234:235], v185 offset:0x1e00
	v_mfma_f32_32x32x16_bf16 v[32:47], v[162:165], v[236:239], v[32:47]
	ds_read_b64_tr_b16 v[236:237], v185 offset:0x2600
	ds_read_b64_tr_b16 v[238:239], v185 offset:0x2e00
	v_mfma_f32_32x32x16_bf16 v[32:47], v[220:223], v[240:243], v[32:47]
	ds_read_b64_tr_b16 v[240:241], v185 offset:0x3600
	ds_read_b64_tr_b16 v[242:243], v185 offset:0x3e00
	s_waitcnt lgkmcnt(0)
	v_mfma_f32_32x32x16_bf16 v[16:31], v[152:155], v[224:227], v[16:31]
	v_max_f32_e32 v152, v81, v81
	v_max_f32_e32 v153, v80, v80
	v_max_f32_e32 v152, v153, v152
	v_max3_f32 v152, v152, v82, v83
	v_max3_f32 v152, v152, v84, v85
	v_max3_f32 v152, v152, v86, v87
	v_max3_f32 v152, v152, v88, v89
	v_max3_f32 v152, v152, v90, v91
	v_mfma_f32_32x32x16_bf16 v[16:31], v[156:159], v[232:235], v[16:31]
	v_max3_f32 v152, v152, v92, v93
	v_max3_f32 v152, v152, v94, v95
	v_max3_f32 v152, v152, v64, v65
	v_max3_f32 v152, v152, v66, v67
	v_max3_f32 v152, v152, v68, v69
	v_max3_f32 v152, v152, v70, v71
	v_max3_f32 v152, v152, v72, v73
	v_max3_f32 v152, v152, v74, v75
	v_mfma_f32_32x32x16_bf16 v[16:31], v[162:165], v[236:239], v[16:31]
	v_max3_f32 v152, v152, v76, v77
	v_max3_f32 v152, v152, v78, v79
	v_mov_b32_e32 v153, v152
	s_nop 1
	v_permlane32_swap_b32_e32 v152, v153
	v_max_f32_e32 v153, v153, v153
	v_max_f32_e32 v152, v152, v152
	v_max_f32_e32 v152, v152, v153
	v_sub_f32_e32 v153, v152, v160
	v_cmp_ge_f32_e32 vcc, s90, v153
	v_max_f32_e32 v153, v160, v160
	v_mfma_f32_32x32x16_bf16 v[16:31], v[220:223], v[240:243], v[16:31]
	v_max_f32_e32 v152, v153, v152
	v_sub_f32_e32 v153, v160, v152
	v_exp_f32_e32 v153, v153
	s_cmp_eq_u64 vcc, exec
	s_cselect_b64 s[0:1], -1, 0
	s_barrier
; #define SWAIT() do { if constexpr (SDEPTH == 2) { if constexpr (DQK == 192) asm volatile("s_waitcnt vmcnt(5)" ::: "memory"); else asm volatile("s_waitcnt vmcnt(4)" ::: "memory"); } \
;     else asm volatile("s_waitcnt vmcnt(0)" ::: "memory"); } while (0)
; #define RESC(a) do { if (__any((a) < 1.f)) { if (hi == 0) al_l[r32] = (a); asm volatile("s_waitcnt lgkmcnt(0)" ::: "memory"); \
;     _Pragma("unroll") for (int d = 0; d < 4; ++d) _Pragma("unroll") for (int r = 0; r < 16; ++r) o[d][r] *= al_h[CROW0(r)]; } } while (0)
; template <int DQK, bool WIN, int SDEPTH, int NQR> ...
;     ...
;         __syncthreads(); SWAIT(); SWRITE(0, SE);
;         RESC(alB); __syncthreads();
	s_waitcnt vmcnt(5)
	v_cndmask_b32_e64 v220, v153, 1.0, s[0:1]
	v_cmp_gt_f32_e32 vcc, 1.0, v220
	s_waitcnt vmcnt(5)
	ds_write_b128 v191, v[120:123]
	ds_write_b128 v195, v[128:131]
	ds_write_b128 v196, v[124:127] offset:32768
	ds_write_b128 v200, v[116:119] offset:32768
	ds_write_b128 v202, v[112:115] offset:32768
	s_cbranch_vccz .LBB0_139
	s_and_saveexec_b64 s[8:9], s[38:39]
	ds_write_b32 v182, v220 offset:128
	s_or_b64 exec, exec, s[8:9]
	s_waitcnt lgkmcnt(0)
	ds_read_b128 v[154:157], v181 offset:224
	ds_read_b128 v[162:165], v181 offset:192
	ds_read_b128 v[222:225], v181 offset:160
	ds_read_b128 v[226:229], v181 offset:128
	s_waitcnt lgkmcnt(3)
	v_pk_mul_f32 v[14:15], v[14:15], v[156:157]
	s_waitcnt lgkmcnt(2)
	v_pk_mul_f32 v[10:11], v[10:11], v[164:165]
	s_waitcnt lgkmcnt(1)
	v_pk_mul_f32 v[6:7], v[6:7], v[224:225]
	s_waitcnt lgkmcnt(0)
	v_pk_mul_f32 v[2:3], v[2:3], v[228:229]
	v_pk_mul_f32 v[12:13], v[12:13], v[154:155]
	v_pk_mul_f32 v[8:9], v[8:9], v[162:163]
	v_pk_mul_f32 v[4:5], v[4:5], v[222:223]
	v_pk_mul_f32 v[0:1], v[0:1], v[226:227]
	v_pk_mul_f32 v[62:63], v[62:63], v[156:157]
	v_pk_mul_f32 v[58:59], v[58:59], v[164:165]
	v_pk_mul_f32 v[54:55], v[54:55], v[224:225]
	v_pk_mul_f32 v[50:51], v[50:51], v[228:229]
	v_pk_mul_f32 v[60:61], v[60:61], v[154:155]
	v_pk_mul_f32 v[56:57], v[56:57], v[162:163]
	v_pk_mul_f32 v[52:53], v[52:53], v[222:223]
	v_pk_mul_f32 v[48:49], v[48:49], v[226:227]
	v_pk_mul_f32 v[46:47], v[46:47], v[156:157]
	v_pk_mul_f32 v[42:43], v[42:43], v[164:165]
	v_pk_mul_f32 v[38:39], v[38:39], v[224:225]
	v_pk_mul_f32 v[34:35], v[34:35], v[228:229]
	v_pk_mul_f32 v[44:45], v[44:45], v[154:155]
	v_pk_mul_f32 v[40:41], v[40:41], v[162:163]
	v_pk_mul_f32 v[36:37], v[36:37], v[222:223]
	v_pk_mul_f32 v[32:33], v[32:33], v[226:227]
	v_pk_mul_f32 v[30:31], v[30:31], v[156:157]
	v_pk_mul_f32 v[26:27], v[26:27], v[164:165]
	v_pk_mul_f32 v[22:23], v[22:23], v[224:225]
	v_pk_mul_f32 v[18:19], v[18:19], v[228:229]
	v_pk_mul_f32 v[28:29], v[28:29], v[154:155]
	v_pk_mul_f32 v[24:25], v[24:25], v[162:163]
	v_pk_mul_f32 v[20:21], v[20:21], v[222:223]
	v_pk_mul_f32 v[16:17], v[16:17], v[226:227]

; #define SBAR() __builtin_amdgcn_sched_barrier(0)
; #define RESC(a) do { if (__any((a) < 1.f)) { if (hi == 0) al_l[r32] = (a); asm volatile("s_waitcnt lgkmcnt(0)" ::: "memory"); \
;     _Pragma("unroll") for (int d = 0; d < 4; ++d) _Pragma("unroll") for (int r = 0; r < 16; ++r) o[d][r] *= al_h[CROW0(r)]; } } while (0)
; #define MASK(P0, P1, t) do { if constexpr (WIN) { const int kb_ = (t) * KVBLK - qpos + 4 * hi; \
;     _Pragma("unroll") for (int r = 0; r < 16; ++r) { const int d_ = kb_ + CROW0(r); if (d_ > 128 || d_ < -128) P0[r] = -1e30f; if (d_ + 32 > 128 || d_ + 32 < -128) P1[r] = -1e30f; } } } while (0)
; __device__ __forceinline__ void partialSM(f32x16& p0, f32x16& p1, float& m_reg, float& mn, float& alpha) {
;     ...
;     if (__builtin_expect(__all(pmax - m_reg <= THRL), 1)) { mn = m_reg; alpha = 1.f; }
;     else { mn = fmaxf(m_reg, pmax); alpha = __builtin_amdgcn_exp2f(m_reg - mn); m_reg = mn; }
; #pragma unroll
;     for (int r = 0; r < 16; ++r) p0[r] = p0[r] - mn;
; #pragma unroll
;     for (int r = 0; r < 16; ++r) p1[r] = p1[r] - mn;
; #pragma unroll
;     for (int r = 0; r < 16; ++r) p0[r] = __builtin_amdgcn_exp2f(p0[r]);
; }
; template <int DQK, bool WIN, int SDEPTH, int NQR> ...
;     ...
;         RESC(alA); __syncthreads();
;     }
;     SBAR(); qkt<DQK, NQR>(pB0, pB1, K_lds + SHM_K, qr, qx, r32, hi); MASK(pB0, pB1, t1 - 1);
.LBB0_145:
	v_cndmask_b32_e64 v160, v153, v221, s[0:1]
	v_sub_f32_e32 v87, v87, v160
	v_exp_f32_e32 v161, v87
	v_sub_f32_e32 v80, v80, v160
	v_sub_f32_e32 v81, v81, v160
	v_sub_f32_e32 v82, v82, v160
	v_sub_f32_e32 v83, v83, v160
	v_sub_f32_e32 v84, v84, v160
	v_sub_f32_e32 v85, v85, v160
	v_sub_f32_e32 v86, v86, v160
	v_sub_f32_e32 v88, v88, v160
	v_sub_f32_e32 v89, v89, v160
	v_sub_f32_e32 v90, v90, v160
	v_sub_f32_e32 v91, v91, v160
	v_sub_f32_e32 v92, v92, v160
	v_sub_f32_e32 v93, v93, v160
	v_sub_f32_e32 v94, v94, v160
	v_sub_f32_e32 v95, v95, v160
	v_exp_f32_e32 v153, v80
	v_exp_f32_e32 v163, v81
	v_exp_f32_e32 v154, v82
	v_exp_f32_e32 v164, v83
	v_exp_f32_e32 v162, v84
	v_exp_f32_e32 v165, v85
	v_exp_f32_e32 v155, v86
	v_exp_f32_e32 v151, v88
	v_exp_f32_e32 v156, v89
	v_exp_f32_e32 v157, v90
	v_exp_f32_e32 v158, v91
	v_exp_f32_e32 v148, v92
	v_exp_f32_e32 v149, v93
	v_exp_f32_e32 v150, v94
	v_exp_f32_e32 v159, v95
	v_pk_add_f32 v[144:145], v[64:65], v[160:161] op_sel_hi:[1,0] neg_lo:[0,1] neg_hi:[0,1]
	v_add_f32_e32 v64, v218, v219
	v_fmac_f32_e32 v64, v217, v183
	v_add_f32_e32 v183, v222, v223
	s_add_i32 s30, s30, 2
	v_pk_add_f32 v[146:147], v[66:67], v[160:161] op_sel_hi:[1,0] neg_lo:[0,1] neg_hi:[0,1]
	v_pk_add_f32 v[136:137], v[68:69], v[160:161] op_sel_hi:[1,0] neg_lo:[0,1] neg_hi:[0,1]
	v_pk_add_f32 v[138:139], v[70:71], v[160:161] op_sel_hi:[1,0] neg_lo:[0,1] neg_hi:[0,1]
	v_pk_add_f32 v[140:141], v[72:73], v[160:161] op_sel_hi:[1,0] neg_lo:[0,1] neg_hi:[0,1]
	v_pk_add_f32 v[142:143], v[74:75], v[160:161] op_sel_hi:[1,0] neg_lo:[0,1] neg_hi:[0,1]
	v_pk_add_f32 v[132:133], v[76:77], v[160:161] op_sel_hi:[1,0] neg_lo:[0,1] neg_hi:[0,1]
	v_pk_add_f32 v[134:135], v[78:79], v[160:161] op_sel_hi:[1,0] neg_lo:[0,1] neg_hi:[0,1]
	v_fmac_f32_e32 v183, v64, v220
	v_add_u32_e32 v174, 0x80, v174
	s_cmp_ge_u32 s30, s31
	v_add_u32_e32 v176, 0x80, v176
	s_waitcnt lgkmcnt(0)
	s_cbranch_scc1 .Lmla_rot_exit
	v_mov_b32_e32 v217, v152
	s_branch .Lmla_head
.Lmla_rot_exit:
	s_barrier
.LBB0_147:
	ds_read_b128 v[64:67], v204 offset:57344
	ds_read_b128 v[68:71], v216 offset:57344
	v_exp_f32_e32 v116, v142
	v_exp_f32_e32 v117, v143
	v_exp_f32_e32 v118, v132
	s_waitcnt lgkmcnt(1)
	v_mfma_f32_32x32x16_bf16 v[80:95], v[64:67], v[108:111], 0
	v_exp_f32_e32 v119, v133
	v_exp_f32_e32 v120, v134
	v_exp_f32_e32 v121, v135
	s_waitcnt lgkmcnt(0)
	v_mfma_f32_32x32x16_bf16 v[64:79], v[68:71], v[108:111], 0
	ds_read_b128 v[108:111], v203 offset:57344
	ds_read_b128 v[112:115], v215 offset:57344
	s_waitcnt lgkmcnt(1)
	v_mfma_f32_32x32x16_bf16 v[80:95], v[108:111], v[104:107], v[80:95]
	s_waitcnt lgkmcnt(0)
	v_mfma_f32_32x32x16_bf16 v[64:79], v[112:115], v[104:107], v[64:79]
	ds_read_b128 v[104:107], v201 offset:57344
	ds_read_b128 v[108:111], v214 offset:57344
	v_exp_f32_e32 v112, v138
	v_exp_f32_e32 v113, v139
	v_exp_f32_e32 v114, v140
	v_exp_f32_e32 v115, v141
	s_waitcnt lgkmcnt(1)
	v_mfma_f32_32x32x16_bf16 v[80:95], v[104:107], v[100:103], v[80:95]
	s_waitcnt lgkmcnt(0)
	v_mfma_f32_32x32x16_bf16 v[64:79], v[108:111], v[100:103], v[64:79]
	ds_read_b128 v[100:103], v198 offset:57344
	ds_read_b128 v[104:107], v213 offset:57344
	v_exp_f32_e32 v108, v146
	v_exp_f32_e32 v109, v147
	v_exp_f32_e32 v110, v136
	v_exp_f32_e32 v111, v137
	s_waitcnt lgkmcnt(1)
	v_mfma_f32_32x32x16_bf16 v[80:95], v[100:103], v[96:99], v[80:95]
	s_waitcnt lgkmcnt(0)
	v_mfma_f32_32x32x16_bf16 v[64:79], v[104:107], v[96:99], v[64:79]
	ds_read_b128 v[96:99], v197 offset:57344
	ds_read_b128 v[100:103], v212 offset:57344
	ds_read_b128 v[104:107], v186
	s_waitcnt lgkmcnt(0)
	v_mfma_f32_32x32x16_bf16 v[80:95], v[96:99], v[104:107], v[80:95]
	v_mfma_f32_32x32x16_bf16 v[64:79], v[100:103], v[104:107], v[64:79]
	ds_read_b128 v[96:99], v199 offset:57344
	ds_read_b128 v[100:103], v211 offset:57344
	ds_read_b128 v[104:107], v186 offset:1024
	s_waitcnt lgkmcnt(0)
	v_mfma_f32_32x32x16_bf16 v[80:95], v[96:99], v[104:107], v[80:95]
	v_mfma_f32_32x32x16_bf16 v[64:79], v[100:103], v[104:107], v[64:79]
	ds_read_b128 v[96:99], v190 offset:57344
	ds_read_b128 v[100:103], v210 offset:57344
	ds_read_b128 v[104:107], v186 offset:2048
	s_waitcnt lgkmcnt(0)
	v_mfma_f32_32x32x16_bf16 v[80:95], v[96:99], v[104:107], v[80:95]
	v_mfma_f32_32x32x16_bf16 v[64:79], v[100:103], v[104:107], v[64:79]
	ds_read_b128 v[96:99], v194 offset:57344
	ds_read_b128 v[100:103], v209 offset:57344
	ds_read_b128 v[104:107], v186 offset:3072
	s_waitcnt lgkmcnt(0)
	v_mfma_f32_32x32x16_bf16 v[80:95], v[96:99], v[104:107], v[80:95]
	v_mfma_f32_32x32x16_bf16 v[64:79], v[100:103], v[104:107], v[64:79]
	ds_read_b128 v[96:99], v187 offset:57344
	ds_read_b128 v[100:103], v208 offset:57344
	ds_read_b128 v[104:107], v186 offset:4096
	s_waitcnt lgkmcnt(0)
	v_mfma_f32_32x32x16_bf16 v[80:95], v[96:99], v[104:107], v[80:95]
	v_mfma_f32_32x32x16_bf16 v[64:79], v[100:103], v[104:107], v[64:79]
	ds_read_b128 v[96:99], v189 offset:57344
	ds_read_b128 v[100:103], v207 offset:57344
	ds_read_b128 v[104:107], v186 offset:5120
	s_waitcnt lgkmcnt(0)
	v_mfma_f32_32x32x16_bf16 v[80:95], v[96:99], v[104:107], v[80:95]
	v_mfma_f32_32x32x16_bf16 v[64:79], v[100:103], v[104:107], v[64:79]
	ds_read_b128 v[96:99], v188 offset:57344
	ds_read_b128 v[100:103], v206 offset:57344
	ds_read_b128 v[104:107], v186 offset:6144
	s_waitcnt lgkmcnt(0)
	v_mfma_f32_32x32x16_bf16 v[80:95], v[96:99], v[104:107], v[80:95]
	v_mfma_f32_32x32x16_bf16 v[64:79], v[100:103], v[104:107], v[64:79]
	ds_read_b128 v[96:99], v205 offset:57344
	ds_read_b128 v[100:103], v192 offset:57344
	ds_read_b128 v[104:107], v186 offset:7168
	s_waitcnt lgkmcnt(0)
; #define SBAR() __builtin_amdgcn_sched_barrier(0)
; #define RESC(a) do { if (__any((a) < 1.f)) { if (hi == 0) al_l[r32] = (a); asm volatile("s_waitcnt lgkmcnt(0)" ::: "memory"); \
;     _Pragma("unroll") for (int d = 0; d < 4; ++d) _Pragma("unroll") for (int r = 0; r < 16; ++r) o[d][r] *= al_h[CROW0(r)]; } } while (0)
; __device__ __forceinline__ void finishSM(f32x16& p0, f32x16& p1, float alpha, float& l_reg, bf16x8& pa0, bf16x8& pa1, bf16x8& pa2, bf16x8& pa3) {
; #pragma unroll
;     for (int r = 0; r < 16; ++r) p1[r] = __builtin_amdgcn_exp2f(p1[r]);
;     float ps = 0;
; #pragma unroll
;     for (int r = 0; r < 16; ++r) ps += p0[r];
; #pragma unroll
;     for (int r = 0; r < 16; ++r) ps += p1[r];
;     { auto rr = __builtin_amdgcn_permlane32_swap(__float_as_uint(ps), __float_as_uint(ps), false, false);
;       ps = __uint_as_float(rr[0]) + __uint_as_float(rr[1]); }
;     l_reg = l_reg * alpha + ps;
;     ...
;     PK4(p0, 0, pa0); PK4(p0, 8, pa1); PK4(p1, 0, pa2); PK4(p1, 8, pa3);
; template <int DQK, bool WIN, int SDEPTH, int NQR> ...
;     ...
;     finishSM(pA0, pA1, alA, l_reg, pa0, pa1, pa2, pa3); SBAR();
;     pv_d0(o, vb0, pa0, pa1, pa2, pa3); partialSM(pB0, pB1, m_reg, mnB, alB);
;     __syncthreads(); RESC(alB);
	v_mfma_f32_32x32x16_bf16 v[80:95], v[96:99], v[104:107], v[80:95]
	v_add_f32_e32 v96, 0, v153
	v_add_f32_e32 v96, v163, v96
	v_add_f32_e32 v96, v154, v96
	v_add_f32_e32 v96, v164, v96
	v_add_f32_e32 v96, v162, v96
	v_add_f32_e32 v96, v165, v96
	v_add_f32_e32 v96, v155, v96
	v_add_f32_e32 v96, v161, v96
	v_add_f32_e32 v96, v151, v96
	v_add_f32_e32 v96, v156, v96
	v_add_f32_e32 v96, v157, v96
	v_add_f32_e32 v96, v158, v96
	v_mfma_f32_32x32x16_bf16 v[64:79], v[100:103], v[104:107], v[64:79]
	v_exp_f32_e32 v106, v144
	v_add_f32_e32 v96, v148, v96
	v_exp_f32_e32 v107, v145
	v_add_f32_e32 v96, v149, v96
	v_add_f32_e32 v96, v150, v96
	v_add_f32_e32 v96, v159, v96
	v_add_f32_e32 v96, v106, v96
	v_add_f32_e32 v96, v107, v96
	v_add_f32_e32 v96, v108, v96
	v_add_f32_e32 v96, v109, v96
	v_add_f32_e32 v96, v110, v96
	v_add_f32_e32 v96, v111, v96
	v_add_f32_e32 v96, v112, v96
	v_add_f32_e32 v96, v113, v96
	v_add_f32_e32 v96, v114, v96
	v_add_f32_e32 v96, v115, v96
	v_add_f32_e32 v96, v116, v96
	v_add_f32_e32 v96, v117, v96
	v_add_f32_e32 v96, v118, v96
	v_add_f32_e32 v96, v119, v96
	v_add_f32_e32 v96, v120, v96
	v_add_f32_e32 v100, v121, v96
	v_mov_b32_e32 v101, v100
	v_cvt_pk_bf16_f32 v96, v153, v163
	v_cvt_pk_bf16_f32 v97, v154, v164
	v_cvt_pk_bf16_f32 v98, v162, v165
	v_cvt_pk_bf16_f32 v99, v155, v161
	s_nop 1
	v_permlane32_swap_b32_e32 v100, v101
	v_permlane32_swap_b32_e32 v96, v98
	v_permlane32_swap_b32_e32 v97, v99
	v_cvt_pk_bf16_f32 v102, v151, v156
	v_cvt_pk_bf16_f32 v103, v157, v158
	v_cvt_pk_bf16_f32 v104, v148, v149
	v_cvt_pk_bf16_f32 v105, v150, v159
	v_cvt_pk_bf16_f32 v106, v106, v107
	v_cvt_pk_bf16_f32 v107, v108, v109
	v_cvt_pk_bf16_f32 v108, v110, v111
	v_cvt_pk_bf16_f32 v109, v112, v113
	v_cvt_pk_bf16_f32 v110, v114, v115
	v_cvt_pk_bf16_f32 v111, v116, v117
	v_cvt_pk_bf16_f32 v112, v118, v119
	v_cvt_pk_bf16_f32 v113, v120, v121
	s_nop 0
	v_permlane32_swap_b32_e32 v102, v104
	v_permlane32_swap_b32_e32 v103, v105
	v_permlane32_swap_b32_e32 v106, v108
	v_permlane32_swap_b32_e32 v107, v109
	v_permlane32_swap_b32_e32 v110, v112
	v_permlane32_swap_b32_e32 v111, v113
	ds_read_b64_tr_b16 v[114:115], v185 offset:0
	ds_read_b64_tr_b16 v[116:117], v185 offset:0x800
	ds_read_b64_tr_b16 v[118:119], v185 offset:0x1000
	ds_read_b64_tr_b16 v[120:121], v185 offset:0x1800
	ds_read_b64_tr_b16 v[122:123], v185 offset:0x2000
	ds_read_b64_tr_b16 v[124:125], v185 offset:0x2800
	ds_read_b64_tr_b16 v[126:127], v185 offset:0x3000
	ds_read_b64_tr_b16 v[128:129], v185 offset:0x3800
	s_waitcnt lgkmcnt(0)
	s_nop 0
	v_mfma_f32_32x32x16_bf16 v[0:15], v[96:99], v[114:117], v[0:15]
	ds_read_b64_tr_b16 v[114:115], v185 offset:0x200
	ds_read_b64_tr_b16 v[116:117], v185 offset:0xa00
	v_mfma_f32_32x32x16_bf16 v[0:15], v[102:105], v[118:121], v[0:15]
	ds_read_b64_tr_b16 v[118:119], v185 offset:0x1200
	ds_read_b64_tr_b16 v[120:121], v185 offset:0x1a00
	v_mfma_f32_32x32x16_bf16 v[0:15], v[106:109], v[122:125], v[0:15]
	ds_read_b64_tr_b16 v[122:123], v185 offset:0x2200
	ds_read_b64_tr_b16 v[124:125], v185 offset:0x2a00
	v_mfma_f32_32x32x16_bf16 v[0:15], v[110:113], v[126:129], v[0:15]
	ds_read_b64_tr_b16 v[126:127], v185 offset:0x3200
	ds_read_b64_tr_b16 v[128:129], v185 offset:0x3a00
	s_waitcnt lgkmcnt(0)
	v_mfma_f32_32x32x16_bf16 v[48:63], v[96:99], v[114:117], v[48:63]
	ds_read_b64_tr_b16 v[114:115], v185 offset:0x400
	ds_read_b64_tr_b16 v[116:117], v185 offset:0xc00
	v_mfma_f32_32x32x16_bf16 v[48:63], v[102:105], v[118:121], v[48:63]
	ds_read_b64_tr_b16 v[118:119], v185 offset:0x1400
	ds_read_b64_tr_b16 v[120:121], v185 offset:0x1c00
	v_mfma_f32_32x32x16_bf16 v[48:63], v[106:109], v[122:125], v[48:63]
	ds_read_b64_tr_b16 v[122:123], v185 offset:0x2400
	ds_read_b64_tr_b16 v[124:125], v185 offset:0x2c00
	v_mfma_f32_32x32x16_bf16 v[48:63], v[110:113], v[126:129], v[48:63]
	ds_read_b64_tr_b16 v[126:127], v185 offset:0x3400
	ds_read_b64_tr_b16 v[128:129], v185 offset:0x3c00
	s_waitcnt lgkmcnt(0)
	v_mfma_f32_32x32x16_bf16 v[32:47], v[96:99], v[114:117], v[32:47]
	ds_read_b64_tr_b16 v[114:115], v185 offset:0x600
	ds_read_b64_tr_b16 v[116:117], v185 offset:0xe00
	v_mfma_f32_32x32x16_bf16 v[32:47], v[102:105], v[118:121], v[32:47]
	ds_read_b64_tr_b16 v[118:119], v185 offset:0x1600
	ds_read_b64_tr_b16 v[120:121], v185 offset:0x1e00
	v_mfma_f32_32x32x16_bf16 v[32:47], v[106:109], v[122:125], v[32:47]
	ds_read_b64_tr_b16 v[122:123], v185 offset:0x2600
	ds_read_b64_tr_b16 v[124:125], v185 offset:0x2e00
	v_mfma_f32_32x32x16_bf16 v[32:47], v[110:113], v[126:129], v[32:47]
	ds_read_b64_tr_b16 v[126:127], v185 offset:0x3600
	ds_read_b64_tr_b16 v[128:129], v185 offset:0x3e00
	s_waitcnt lgkmcnt(0)
	v_mfma_f32_32x32x16_bf16 v[16:31], v[96:99], v[114:117], v[16:31]
	v_max_f32_e32 v96, v81, v81
	v_max_f32_e32 v97, v80, v80
	v_max_f32_e32 v96, v97, v96
	v_max3_f32 v96, v96, v82, v83
	v_max3_f32 v96, v96, v84, v85
	v_max3_f32 v96, v96, v86, v87
	v_max3_f32 v96, v96, v88, v89
	v_max3_f32 v96, v96, v90, v91
	v_mfma_f32_32x32x16_bf16 v[16:31], v[102:105], v[118:121], v[16:31]
	v_max3_f32 v96, v96, v92, v93
	v_max3_f32 v96, v96, v94, v95
	v_max3_f32 v96, v96, v64, v65
	v_max3_f32 v96, v96, v66, v67
	v_max3_f32 v96, v96, v68, v69
	v_max3_f32 v96, v96, v70, v71
	v_max3_f32 v96, v96, v72, v73
	v_max3_f32 v96, v96, v74, v75
	v_mfma_f32_32x32x16_bf16 v[16:31], v[106:109], v[122:125], v[16:31]
	v_max3_f32 v96, v96, v76, v77
	v_max3_f32 v96, v96, v78, v79
	v_mov_b32_e32 v97, v96
	s_nop 1
	v_permlane32_swap_b32_e32 v96, v97
	v_max_f32_e32 v97, v97, v97
	v_max_f32_e32 v96, v96, v96
	v_max_f32_e32 v96, v96, v97
	v_sub_f32_e32 v97, v96, v160
	v_cmp_ge_f32_e32 vcc, s90, v97
	v_max_f32_e32 v97, v160, v160
	v_mfma_f32_32x32x16_bf16 v[16:31], v[110:113], v[126:129], v[16:31]
	v_max_f32_e32 v97, v97, v96
	v_sub_f32_e32 v96, v160, v97
	v_exp_f32_e32 v96, v96
	s_cmp_eq_u64 vcc, exec
	s_cselect_b64 s[0:1], -1, 0
	v_cndmask_b32_e64 v96, v96, 1.0, s[0:1]
	v_cmp_gt_f32_e32 vcc, 1.0, v96
	s_barrier
; #define RESC(a) do { if (__any((a) < 1.f)) { if (hi == 0) al_l[r32] = (a); asm volatile("s_waitcnt lgkmcnt(0)" ::: "memory"); \
;     _Pragma("unroll") for (int d = 0; d < 4; ++d) _Pragma("unroll") for (int r = 0; r < 16; ++r) o[d][r] *= al_h[CROW0(r)]; } } while (0)
; template <int DQK, bool WIN, int SDEPTH, int NQR> ...
;     ...
;     __syncthreads(); RESC(alB);
	s_cbranch_vccz .LBB0_151
	s_and_saveexec_b64 s[8:9], s[38:39]
	ds_write_b32 v182, v96 offset:128
	s_or_b64 exec, exec, s[8:9]
	s_waitcnt lgkmcnt(0)
	ds_read_b128 v[102:105], v181 offset:224
	ds_read_b128 v[106:109], v181 offset:192
	ds_read_b128 v[110:113], v181 offset:160
	ds_read_b128 v[114:117], v181 offset:128
	s_waitcnt lgkmcnt(3)
	v_pk_mul_f32 v[14:15], v[14:15], v[104:105]
	s_waitcnt lgkmcnt(2)
	v_pk_mul_f32 v[10:11], v[10:11], v[108:109]
	s_waitcnt lgkmcnt(1)
	v_pk_mul_f32 v[6:7], v[6:7], v[112:113]
	s_waitcnt lgkmcnt(0)
	v_pk_mul_f32 v[2:3], v[2:3], v[116:117]
	v_pk_mul_f32 v[12:13], v[12:13], v[102:103]
	v_pk_mul_f32 v[8:9], v[8:9], v[106:107]
	v_pk_mul_f32 v[4:5], v[4:5], v[110:111]
	v_pk_mul_f32 v[0:1], v[0:1], v[114:115]
	v_pk_mul_f32 v[62:63], v[62:63], v[104:105]
	v_pk_mul_f32 v[58:59], v[58:59], v[108:109]
	v_pk_mul_f32 v[54:55], v[54:55], v[112:113]
	v_pk_mul_f32 v[50:51], v[50:51], v[116:117]
	v_pk_mul_f32 v[60:61], v[60:61], v[102:103]
	v_pk_mul_f32 v[56:57], v[56:57], v[106:107]
	v_pk_mul_f32 v[52:53], v[52:53], v[110:111]
	v_pk_mul_f32 v[48:49], v[48:49], v[114:115]
	v_pk_mul_f32 v[46:47], v[46:47], v[104:105]
	v_pk_mul_f32 v[42:43], v[42:43], v[108:109]
	v_pk_mul_f32 v[38:39], v[38:39], v[112:113]
	v_pk_mul_f32 v[34:35], v[34:35], v[116:117]
	v_pk_mul_f32 v[44:45], v[44:45], v[102:103]
	v_pk_mul_f32 v[40:41], v[40:41], v[106:107]
	v_pk_mul_f32 v[36:37], v[36:37], v[110:111]
	v_pk_mul_f32 v[32:33], v[32:33], v[114:115]
	v_pk_mul_f32 v[30:31], v[30:31], v[104:105]
	v_pk_mul_f32 v[26:27], v[26:27], v[108:109]
	v_pk_mul_f32 v[22:23], v[22:23], v[112:113]
	v_pk_mul_f32 v[18:19], v[18:19], v[116:117]
	v_pk_mul_f32 v[28:29], v[28:29], v[102:103]
	v_pk_mul_f32 v[24:25], v[24:25], v[106:107]
	v_pk_mul_f32 v[20:21], v[20:21], v[110:111]
	v_pk_mul_f32 v[16:17], v[16:17], v[114:115]
